# hyena ctx conv: tap rows staged with all loads in flight (was load-wait-write per row)
# speedup vs baseline: 1.0185x; 1.0054x over previous
; template <int LS>
; __device__ __forceinline__ void hyena_item(const Params& p, int l, int b, int cg, int tb, bool isctx, LAS unsigned char* lds) {
;     ...
;               zs[(wid * 8 + k) * 64 + lane] = (wva * pv0 + wvb * pv1 + wvc * pv2) * (wx1a * px0 + wx1b * px1 + wx1c * px2);
;               pv0 = pv1; pv1 = pv2; px0 = px1; px1 = px2; } }
;         { const int jlo = tblk - sc - 63 + LS - 1;
; #pragma unroll 8
;           for (int r = wid; r < 319; r += 8) { const int j = jlo + r; fs[r * 64 + lane] = (j >= 0 && j <= 2 * LS - 2) ? FX[(size_t)j * 512 + lane] : 0.f; } }
.LBB0_890:
	v_pk_mul_f32 v[54:55], v[10:11], v[62:63]
	s_andn2_b64 vcc, exec, s[6:7]
	v_pk_fma_f32 v[54:55], v[6:7], v[56:57], v[54:55]
	s_nop 0
	v_pk_fma_f32 v[54:55], v[8:9], v[58:59], v[54:55]
	s_nop 0
	v_mul_f32_e32 v47, v54, v55
	ds_write_b32 v0, v47 offset:1792
	s_cbranch_vccnz .LBB0_915
	s_add_i32 s3, s26, s18
	v_lshl_add_u32 v211, s3, 9, v42
	v_lshlrev_b32_e32 v211, 2, v211
	v_lshl_add_u32 v212, s18, 8, v45
	v_add_u32_e32 v169, 0x10000, v212
	v_mov_b32_e32 v171, 0
	v_mov_b32_e32 v172, 0
	v_mov_b32_e32 v173, 0
	v_mov_b32_e32 v174, 0
	v_mov_b32_e32 v175, 0
	v_mov_b32_e32 v176, 0
	v_mov_b32_e32 v177, 0
	v_mov_b32_e32 v178, 0
	v_mov_b32_e32 v179, 0
	v_mov_b32_e32 v180, 0
	v_mov_b32_e32 v181, 0
	v_mov_b32_e32 v182, 0
	v_mov_b32_e32 v183, 0
	v_mov_b32_e32 v184, 0
	v_mov_b32_e32 v185, 0
	v_mov_b32_e32 v186, 0
	v_mov_b32_e32 v187, 0
	v_mov_b32_e32 v188, 0
	v_mov_b32_e32 v189, 0
	v_mov_b32_e32 v190, 0
	v_mov_b32_e32 v191, 0
	v_mov_b32_e32 v192, 0
	v_mov_b32_e32 v193, 0
	v_mov_b32_e32 v194, 0
	v_mov_b32_e32 v195, 0
	v_mov_b32_e32 v196, 0
	v_mov_b32_e32 v197, 0
	v_mov_b32_e32 v198, 0
	v_mov_b32_e32 v199, 0
	v_mov_b32_e32 v200, 0
	v_mov_b32_e32 v201, 0
	v_mov_b32_e32 v202, 0
	v_mov_b32_e32 v203, 0
	v_mov_b32_e32 v204, 0
	v_mov_b32_e32 v205, 0
	v_mov_b32_e32 v206, 0
	v_mov_b32_e32 v207, 0
	v_mov_b32_e32 v208, 0
	v_mov_b32_e32 v209, 0
	v_mov_b32_e32 v210, 0
	s_add_i32 s40, s3, 0
	s_cmpk_gt_u32 s40, 0x1fe
	s_cbranch_scc1 .Lhfs_sk0
	global_load_dword v171, v211, s[4:5]
.Lhfs_sk0:
	v_add_u32_e32 v211, 0x4000, v211
	s_add_i32 s40, s3, 8
	s_cmpk_gt_u32 s40, 0x1fe
	s_cbranch_scc1 .Lhfs_sk1
	global_load_dword v172, v211, s[4:5]
.Lhfs_sk1:
	v_add_u32_e32 v211, 0x4000, v211
	s_add_i32 s40, s3, 16
	s_cmpk_gt_u32 s40, 0x1fe
	s_cbranch_scc1 .Lhfs_sk2
	global_load_dword v173, v211, s[4:5]
.Lhfs_sk2:
	v_add_u32_e32 v211, 0x4000, v211
	s_add_i32 s40, s3, 24
	s_cmpk_gt_u32 s40, 0x1fe
	s_cbranch_scc1 .Lhfs_sk3
	global_load_dword v174, v211, s[4:5]
.Lhfs_sk3:
	v_add_u32_e32 v211, 0x4000, v211
	s_add_i32 s40, s3, 32
	s_cmpk_gt_u32 s40, 0x1fe
	s_cbranch_scc1 .Lhfs_sk4
	global_load_dword v175, v211, s[4:5]
.Lhfs_sk4:
	v_add_u32_e32 v211, 0x4000, v211
	s_add_i32 s40, s3, 40
	s_cmpk_gt_u32 s40, 0x1fe
	s_cbranch_scc1 .Lhfs_sk5
	global_load_dword v176, v211, s[4:5]
.Lhfs_sk5:
	v_add_u32_e32 v211, 0x4000, v211
	s_add_i32 s40, s3, 48
	s_cmpk_gt_u32 s40, 0x1fe
	s_cbranch_scc1 .Lhfs_sk6
	global_load_dword v177, v211, s[4:5]
.Lhfs_sk6:
	v_add_u32_e32 v211, 0x4000, v211
	s_add_i32 s40, s3, 56
	s_cmpk_gt_u32 s40, 0x1fe
	s_cbranch_scc1 .Lhfs_sk7
	global_load_dword v178, v211, s[4:5]
.Lhfs_sk7:
	v_add_u32_e32 v211, 0x4000, v211
	s_add_i32 s40, s3, 64
	s_cmpk_gt_u32 s40, 0x1fe
	s_cbranch_scc1 .Lhfs_sk8
	global_load_dword v179, v211, s[4:5]
.Lhfs_sk8:
	v_add_u32_e32 v211, 0x4000, v211
	s_add_i32 s40, s3, 0x48
	s_cmpk_gt_u32 s40, 0x1fe
	s_cbranch_scc1 .Lhfs_sk9
	global_load_dword v180, v211, s[4:5]
.Lhfs_sk9:
	v_add_u32_e32 v211, 0x4000, v211
	s_add_i32 s40, s3, 0x50
	s_cmpk_gt_u32 s40, 0x1fe
	s_cbranch_scc1 .Lhfs_sk10
	global_load_dword v181, v211, s[4:5]
.Lhfs_sk10:
	v_add_u32_e32 v211, 0x4000, v211
	s_add_i32 s40, s3, 0x58
	s_cmpk_gt_u32 s40, 0x1fe
	s_cbranch_scc1 .Lhfs_sk11
	global_load_dword v182, v211, s[4:5]
.Lhfs_sk11:
	v_add_u32_e32 v211, 0x4000, v211
	s_add_i32 s40, s3, 0x60
	s_cmpk_gt_u32 s40, 0x1fe
	s_cbranch_scc1 .Lhfs_sk12
	global_load_dword v183, v211, s[4:5]
.Lhfs_sk12:
	v_add_u32_e32 v211, 0x4000, v211
	s_add_i32 s40, s3, 0x68
	s_cmpk_gt_u32 s40, 0x1fe
	s_cbranch_scc1 .Lhfs_sk13
	global_load_dword v184, v211, s[4:5]
.Lhfs_sk13:
	v_add_u32_e32 v211, 0x4000, v211
	s_add_i32 s40, s3, 0x70
	s_cmpk_gt_u32 s40, 0x1fe
	s_cbranch_scc1 .Lhfs_sk14
	global_load_dword v185, v211, s[4:5]
.Lhfs_sk14:
	v_add_u32_e32 v211, 0x4000, v211
	s_add_i32 s40, s3, 0x78
	s_cmpk_gt_u32 s40, 0x1fe
	s_cbranch_scc1 .Lhfs_sk15
	global_load_dword v186, v211, s[4:5]
.Lhfs_sk15:
	v_add_u32_e32 v211, 0x4000, v211
	s_add_i32 s40, s3, 0x80
	s_cmpk_gt_u32 s40, 0x1fe
	s_cbranch_scc1 .Lhfs_sk16
	global_load_dword v187, v211, s[4:5]
.Lhfs_sk16:
	v_add_u32_e32 v211, 0x4000, v211
	s_add_i32 s40, s3, 0x88
	s_cmpk_gt_u32 s40, 0x1fe
	s_cbranch_scc1 .Lhfs_sk17
	global_load_dword v188, v211, s[4:5]
.Lhfs_sk17:
	v_add_u32_e32 v211, 0x4000, v211
	s_add_i32 s40, s3, 0x90
	s_cmpk_gt_u32 s40, 0x1fe
	s_cbranch_scc1 .Lhfs_sk18
	global_load_dword v189, v211, s[4:5]
.Lhfs_sk18:
	v_add_u32_e32 v211, 0x4000, v211
	s_add_i32 s40, s3, 0x98
	s_cmpk_gt_u32 s40, 0x1fe
	s_cbranch_scc1 .Lhfs_sk19
	global_load_dword v190, v211, s[4:5]
.Lhfs_sk19:
	v_add_u32_e32 v211, 0x4000, v211
	s_add_i32 s40, s3, 0xa0
	s_cmpk_gt_u32 s40, 0x1fe
	s_cbranch_scc1 .Lhfs_sk20
	global_load_dword v191, v211, s[4:5]
; template <int LS>
; __device__ __forceinline__ void hyena_item(const Params& p, int l, int b, int cg, int tb, bool isctx, LAS unsigned char* lds) {
;     ...
;         { const int jlo = tblk - sc - 63 + LS - 1;
; #pragma unroll 8
;           for (int r = wid; r < 319; r += 8) { const int j = jlo + r; fs[r * 64 + lane] = (j >= 0 && j <= 2 * LS - 2) ? FX[(size_t)j * 512 + lane] : 0.f; } }
.Lhfs_sk20:
	v_add_u32_e32 v211, 0x4000, v211
	s_add_i32 s40, s3, 0xa8
	s_cmpk_gt_u32 s40, 0x1fe
	s_cbranch_scc1 .Lhfs_sk21
	global_load_dword v192, v211, s[4:5]
.Lhfs_sk21:
	v_add_u32_e32 v211, 0x4000, v211
	s_add_i32 s40, s3, 0xb0
	s_cmpk_gt_u32 s40, 0x1fe
	s_cbranch_scc1 .Lhfs_sk22
	global_load_dword v193, v211, s[4:5]
.Lhfs_sk22:
	v_add_u32_e32 v211, 0x4000, v211
	s_add_i32 s40, s3, 0xb8
	s_cmpk_gt_u32 s40, 0x1fe
	s_cbranch_scc1 .Lhfs_sk23
	global_load_dword v194, v211, s[4:5]
.Lhfs_sk23:
	v_add_u32_e32 v211, 0x4000, v211
	s_add_i32 s40, s3, 0xc0
	s_cmpk_gt_u32 s40, 0x1fe
	s_cbranch_scc1 .Lhfs_sk24
	global_load_dword v195, v211, s[4:5]
.Lhfs_sk24:
	v_add_u32_e32 v211, 0x4000, v211
	s_add_i32 s40, s3, 0xc8
	s_cmpk_gt_u32 s40, 0x1fe
	s_cbranch_scc1 .Lhfs_sk25
	global_load_dword v196, v211, s[4:5]
.Lhfs_sk25:
	v_add_u32_e32 v211, 0x4000, v211
	s_add_i32 s40, s3, 0xd0
	s_cmpk_gt_u32 s40, 0x1fe
	s_cbranch_scc1 .Lhfs_sk26
	global_load_dword v197, v211, s[4:5]
.Lhfs_sk26:
	v_add_u32_e32 v211, 0x4000, v211
	s_add_i32 s40, s3, 0xd8
	s_cmpk_gt_u32 s40, 0x1fe
	s_cbranch_scc1 .Lhfs_sk27
	global_load_dword v198, v211, s[4:5]
.Lhfs_sk27:
	v_add_u32_e32 v211, 0x4000, v211
	s_add_i32 s40, s3, 0xe0
	s_cmpk_gt_u32 s40, 0x1fe
	s_cbranch_scc1 .Lhfs_sk28
	global_load_dword v199, v211, s[4:5]
.Lhfs_sk28:
	v_add_u32_e32 v211, 0x4000, v211
	s_add_i32 s40, s3, 0xe8
	s_cmpk_gt_u32 s40, 0x1fe
	s_cbranch_scc1 .Lhfs_sk29
	global_load_dword v200, v211, s[4:5]
.Lhfs_sk29:
	v_add_u32_e32 v211, 0x4000, v211
	s_add_i32 s40, s3, 0xf0
	s_cmpk_gt_u32 s40, 0x1fe
	s_cbranch_scc1 .Lhfs_sk30
	global_load_dword v201, v211, s[4:5]
.Lhfs_sk30:
	v_add_u32_e32 v211, 0x4000, v211
	s_add_i32 s40, s3, 0xf8
	s_cmpk_gt_u32 s40, 0x1fe
	s_cbranch_scc1 .Lhfs_sk31
	global_load_dword v202, v211, s[4:5]
.Lhfs_sk31:
	v_add_u32_e32 v211, 0x4000, v211
	s_add_i32 s40, s3, 0x100
	s_cmpk_gt_u32 s40, 0x1fe
	s_cbranch_scc1 .Lhfs_sk32
	global_load_dword v203, v211, s[4:5]
.Lhfs_sk32:
	v_add_u32_e32 v211, 0x4000, v211
	s_add_i32 s40, s3, 0x108
	s_cmpk_gt_u32 s40, 0x1fe
	s_cbranch_scc1 .Lhfs_sk33
	global_load_dword v204, v211, s[4:5]
.Lhfs_sk33:
	v_add_u32_e32 v211, 0x4000, v211
	s_add_i32 s40, s3, 0x110
	s_cmpk_gt_u32 s40, 0x1fe
	s_cbranch_scc1 .Lhfs_sk34
	global_load_dword v205, v211, s[4:5]
.Lhfs_sk34:
	v_add_u32_e32 v211, 0x4000, v211
	s_add_i32 s40, s3, 0x118
	s_cmpk_gt_u32 s40, 0x1fe
	s_cbranch_scc1 .Lhfs_sk35
	global_load_dword v206, v211, s[4:5]
.Lhfs_sk35:
	v_add_u32_e32 v211, 0x4000, v211
	s_add_i32 s40, s3, 0x120
	s_cmpk_gt_u32 s40, 0x1fe
	s_cbranch_scc1 .Lhfs_sk36
	global_load_dword v207, v211, s[4:5]
.Lhfs_sk36:
	v_add_u32_e32 v211, 0x4000, v211
	s_add_i32 s40, s3, 0x128
	s_cmpk_gt_u32 s40, 0x1fe
	s_cbranch_scc1 .Lhfs_sk37
	global_load_dword v208, v211, s[4:5]
.Lhfs_sk37:
	v_add_u32_e32 v211, 0x4000, v211
	s_add_i32 s40, s3, 0x130
	s_cmpk_gt_u32 s40, 0x1fe
	s_cbranch_scc1 .Lhfs_sk38
	global_load_dword v209, v211, s[4:5]
.Lhfs_sk38:
	v_add_u32_e32 v211, 0x4000, v211
	s_cmp_gt_u32 s18, 6
	s_cbranch_scc1 .Lhfs_ld_done
	s_add_i32 s40, s3, 0x138
	s_cmpk_gt_u32 s40, 0x1fe
	s_cbranch_scc1 .Lhfs_sk39
	global_load_dword v210, v211, s[4:5]
.Lhfs_sk39:
.Lhfs_ld_done:
	s_waitcnt vmcnt(0)
	ds_write_b32 v212, v171
	ds_write_b32 v212, v172 offset:2048
	ds_write_b32 v212, v173 offset:4096
	ds_write_b32 v212, v174 offset:6144
	ds_write_b32 v212, v175 offset:8192
	ds_write_b32 v212, v176 offset:10240
	ds_write_b32 v212, v177 offset:12288
	ds_write_b32 v212, v178 offset:14336
	ds_write_b32 v212, v179 offset:16384
	ds_write_b32 v212, v180 offset:18432
	ds_write_b32 v212, v181 offset:20480
	ds_write_b32 v212, v182 offset:22528
	ds_write_b32 v212, v183 offset:24576
	ds_write_b32 v212, v184 offset:26624
	ds_write_b32 v212, v185 offset:28672
	ds_write_b32 v212, v186 offset:30720
	ds_write_b32 v212, v187 offset:32768
	ds_write_b32 v212, v188 offset:34816
	ds_write_b32 v212, v189 offset:36864
	ds_write_b32 v212, v190 offset:38912
	ds_write_b32 v212, v191 offset:40960
	ds_write_b32 v212, v192 offset:43008
	ds_write_b32 v212, v193 offset:45056
	ds_write_b32 v212, v194 offset:47104
	ds_write_b32 v212, v195 offset:49152
	ds_write_b32 v212, v196 offset:51200
	ds_write_b32 v212, v197 offset:53248
	ds_write_b32 v212, v198 offset:55296
	ds_write_b32 v212, v199 offset:57344
	ds_write_b32 v212, v200 offset:59392
	ds_write_b32 v212, v201 offset:61440
	ds_write_b32 v212, v202 offset:63488
	ds_write_b32 v169, v203
	ds_write_b32 v169, v204 offset:2048
	ds_write_b32 v169, v205 offset:4096
	ds_write_b32 v169, v206 offset:6144
	ds_write_b32 v169, v207 offset:8192
	ds_write_b32 v169, v208 offset:10240
	ds_write_b32 v169, v209 offset:12288
	s_cmp_gt_u32 s18, 6
	s_cbranch_scc1 .LBB0_915
	ds_write_b32 v169, v210 offset:14336
